# P0 rebalance with meta workgroups keeping 7 of 8 RMSNorm iterations (no transposes) + g1 hoist
# baseline (speedup 1.0000x reference)
.Lmy_p0_bdisp:
	s_cmp_lg_u32 s33, 0x100
	s_cbranch_scc1 .LBB0_49
	s_cmp_lg_u32 s60, 1
	s_cbranch_scc1 .Lmy_p0_bx
	s_mov_b32 s60, 2
	s_mov_b32 s4, s61
	s_mov_b32 s62, 0x8000
	s_cmp_lt_u32 s63, 0x50
	s_cbranch_scc0 .Lmy_p0_b43
	s_add_u32 s62, s61, 0x7000
	s_branch .Lmy_p0_b43
.Lmy_p0_bx:
	s_cmp_lt_u32 s63, 0x50
	s_cbranch_scc1 .LBB0_49
	s_cmp_gt_u32 s60, 4
	s_cbranch_scc1 .LBB0_49
	s_sub_u32 s65, s60, 2
	s_mul_i32 s65, s65, 0xb0
	s_add_u32 s65, s65, s63
	s_sub_u32 s65, s65, 0x50
	s_add_u32 s60, s60, 1
	s_cmp_ge_u32 s65, 0x50
	s_cbranch_scc1 .LBB0_49
	s_mul_i32 s66, s65, 0xcd
	s_lshr_b32 s66, s66, 14
	s_mul_i32 s67, s66, 0x50
	s_sub_u32 s65, s65, s67
	s_add_u32 s66, s66, 7
	s_lshl_b32 s66, s66, 12
	s_lshl_b32 s4, s64, 8
	s_add_u32 s4, s4, s65
	s_add_u32 s4, s4, s66
	s_add_u32 s62, s4, 1
	s_mov_b64 s[14:15], s[68:69]
	s_mov_b64 s[16:17], s[70:71]
	s_mov_b64 s[8:9], s[72:73]
